# GEMM unit boundaries: accumulator VGPRs zeroed once per output tile instead of twice (hipcc's dead first run moved out of line), 9 GEMM instances; on top of MLA K read-ahead
# baseline (speedup 1.0000x reference)
; template <class Epi, class Sched, bool ALIGN_EPI = false, bool SP2 = false>
; __device__ __forceinline__ void gemm_phase(PG8_LAS unsigned char* lds, const Gemm g, const Sched& S, const Epi& E, const int tid_in) {
;     ...
; #pragma unroll
;         for (int a = 0; a < 2; ++a)
; #pragma unroll
;             for (int b = 0; b < 2; ++b)
; #pragma unroll
;                 for (int m = 0; m < 4; ++m)
; #pragma unroll
;                     for (int n = 0; n < 2; ++n) acc[a][b][m][n] = (f32x4){0.f, 0.f, 0.f, 0.f};
;         cur = nxt; cA = nA; cB = nB; ++ui;
.Lzk_1:
	v_mov_b32_e32 v127, 0
	v_mov_b32_e32 v126, v127
	v_mov_b32_e32 v125, v127
	v_mov_b32_e32 v124, v127
	v_mov_b32_e32 v123, v127
	v_mov_b32_e32 v122, v127
	v_mov_b32_e32 v121, v127
	v_mov_b32_e32 v120, v127
	v_mov_b32_e32 v111, v127
	v_mov_b32_e32 v110, v127
	v_mov_b32_e32 v109, v127
	v_mov_b32_e32 v108, v127
	v_mov_b32_e32 v107, v127
	v_mov_b32_e32 v106, v127
	v_mov_b32_e32 v105, v127
	v_mov_b32_e32 v104, v127
	v_mov_b32_e32 v95, v127
	v_mov_b32_e32 v94, v127
	v_mov_b32_e32 v93, v127
	v_mov_b32_e32 v92, v127
	v_mov_b32_e32 v91, v127
	v_mov_b32_e32 v90, v127
	v_mov_b32_e32 v89, v127
	v_mov_b32_e32 v88, v127
	v_mov_b32_e32 v79, v127
	v_mov_b32_e32 v78, v127
	v_mov_b32_e32 v77, v127
	v_mov_b32_e32 v76, v127
	v_mov_b32_e32 v75, v127
	v_mov_b32_e32 v74, v127
	v_mov_b32_e32 v73, v127
	v_mov_b32_e32 v72, v127
	v_mov_b32_e32 v119, v127
	v_mov_b32_e32 v118, v127
	v_mov_b32_e32 v117, v127
	v_mov_b32_e32 v116, v127
	v_mov_b32_e32 v115, v127
	v_mov_b32_e32 v114, v127
	v_mov_b32_e32 v113, v127
	v_mov_b32_e32 v112, v127
	v_mov_b32_e32 v103, v127
	v_mov_b32_e32 v102, v127
	v_mov_b32_e32 v101, v127
	v_mov_b32_e32 v100, v127
	v_mov_b32_e32 v99, v127
	v_mov_b32_e32 v98, v127
	v_mov_b32_e32 v97, v127
	v_mov_b32_e32 v96, v127
	v_mov_b32_e32 v87, v127
	v_mov_b32_e32 v86, v127
	v_mov_b32_e32 v85, v127
	v_mov_b32_e32 v84, v127
	v_mov_b32_e32 v83, v127
	v_mov_b32_e32 v82, v127
	v_mov_b32_e32 v81, v127
	v_mov_b32_e32 v80, v127
	v_mov_b32_e32 v71, v127
	v_mov_b32_e32 v70, v127
	v_mov_b32_e32 v69, v127
	v_mov_b32_e32 v68, v127
	v_mov_b32_e32 v67, v127
	v_mov_b32_e32 v66, v127
	v_mov_b32_e32 v65, v127
	v_mov_b32_e32 v64, v127
	v_mov_b32_e32 v63, v127
	v_mov_b32_e32 v62, v127
	v_mov_b32_e32 v61, v127
	v_mov_b32_e32 v60, v127
	v_mov_b32_e32 v59, v127
	v_mov_b32_e32 v58, v127
	v_mov_b32_e32 v57, v127
	v_mov_b32_e32 v56, v127
	v_mov_b32_e32 v47, v127
	v_mov_b32_e32 v46, v127
	v_mov_b32_e32 v45, v127
	v_mov_b32_e32 v44, v127
	v_mov_b32_e32 v43, v127
	v_mov_b32_e32 v42, v127
	v_mov_b32_e32 v41, v127
	v_mov_b32_e32 v40, v127
	v_mov_b32_e32 v31, v127
	v_mov_b32_e32 v30, v127
	v_mov_b32_e32 v29, v127
	v_mov_b32_e32 v28, v127
	v_mov_b32_e32 v27, v127
	v_mov_b32_e32 v26, v127
	v_mov_b32_e32 v25, v127
	v_mov_b32_e32 v24, v127
	v_mov_b32_e32 v15, v127
	v_mov_b32_e32 v14, v127
	v_mov_b32_e32 v13, v127
	v_mov_b32_e32 v12, v127
	v_mov_b32_e32 v11, v127
	v_mov_b32_e32 v10, v127
	v_mov_b32_e32 v9, v127
	v_mov_b32_e32 v8, v127
	v_mov_b32_e32 v55, v127
	v_mov_b32_e32 v54, v127
	v_mov_b32_e32 v53, v127
	v_mov_b32_e32 v52, v127
	v_mov_b32_e32 v51, v127
	v_mov_b32_e32 v50, v127
	v_mov_b32_e32 v49, v127
	v_mov_b32_e32 v48, v127
	v_mov_b32_e32 v39, v127
	v_mov_b32_e32 v38, v127
	v_mov_b32_e32 v37, v127
	v_mov_b32_e32 v36, v127
	v_mov_b32_e32 v35, v127
	v_mov_b32_e32 v34, v127
	v_mov_b32_e32 v33, v127
	v_mov_b32_e32 v32, v127
	v_mov_b32_e32 v23, v127
	v_mov_b32_e32 v22, v127
	v_mov_b32_e32 v21, v127
	v_mov_b32_e32 v20, v127
	v_mov_b32_e32 v19, v127
	v_mov_b32_e32 v18, v127
	v_mov_b32_e32 v17, v127
	v_mov_b32_e32 v16, v127
	v_mov_b32_e32 v7, v127
	v_mov_b32_e32 v6, v127
	v_mov_b32_e32 v5, v127
	v_mov_b32_e32 v4, v127
	v_mov_b32_e32 v3, v127
	v_mov_b32_e32 v2, v127
	v_mov_b32_e32 v1, v127
	v_mov_b32_e32 v0, v127
	s_branch .LBB0_239

; template <class Epi, class Sched, bool ALIGN_EPI = false, bool SP2 = false>
; __device__ __forceinline__ void gemm_phase(PG8_LAS unsigned char* lds, const Gemm g, const Sched& S, const Epi& E, const int tid_in) {
;     ...
;         for (int t = 0; t < nt; t += 2) {
;             const bool last = (t == nt - 2);
;             const char* a1 = cA + (size_t)(t + 1) * kstep;
;             const char* a2 = last ? nA : cA + (size_t)(t + 2) * kstep; const char* b2 = last ? nB : cB + (size_t)(t + 2) * kstep;
;             const char* a3 = a2 + kstep; const char* b3 = b2 + kstep;
;     ...
; #pragma unroll
;         for (int a = 0; a < 2; ++a)
; #pragma unroll
;             for (int b = 0; b < 2; ++b)
; #pragma unroll
;                 for (int m = 0; m < 4; ++m)
; #pragma unroll
;                     for (int n = 0; n < 2; ++n) acc[a][b][m][n] = (f32x4){0.f, 0.f, 0.f, 0.f};
;         cur = nxt; cA = nA; cB = nB; ++ui;
.LBB0_235:
	s_andn2_b64 vcc, exec, s[14:15]
	s_cbranch_vccnz .Lzk_1
	s_add_u32 s20, s20, 0x80
	s_addc_u32 s21, s21, 0
	s_add_u32 s49, s22, 0x100
	v_mov_b32_e32 v0, 0
	s_addc_u32 s50, s23, 0
	s_mov_b32 s22, 0
	v_mov_b32_e32 v1, v0
	v_mov_b32_e32 v2, v0
	v_mov_b32_e32 v3, v0
	v_mov_b32_e32 v4, v0
	v_mov_b32_e32 v5, v0
	v_mov_b32_e32 v6, v0
	v_mov_b32_e32 v7, v0
	v_mov_b32_e32 v16, v0
	v_mov_b32_e32 v17, v0
	v_mov_b32_e32 v18, v0
	v_mov_b32_e32 v19, v0
	v_mov_b32_e32 v20, v0
	v_mov_b32_e32 v21, v0
	v_mov_b32_e32 v22, v0
	v_mov_b32_e32 v23, v0
	v_mov_b32_e32 v32, v0
	v_mov_b32_e32 v33, v0
	v_mov_b32_e32 v34, v0
	v_mov_b32_e32 v35, v0
	v_mov_b32_e32 v36, v0
	v_mov_b32_e32 v37, v0
	v_mov_b32_e32 v38, v0
	v_mov_b32_e32 v39, v0
	v_mov_b32_e32 v48, v0
	v_mov_b32_e32 v49, v0
	v_mov_b32_e32 v50, v0
	v_mov_b32_e32 v51, v0
	v_mov_b32_e32 v52, v0
	v_mov_b32_e32 v53, v0
	v_mov_b32_e32 v54, v0
	v_mov_b32_e32 v55, v0
	v_mov_b32_e32 v8, v0
	v_mov_b32_e32 v9, v0
	v_mov_b32_e32 v10, v0
	v_mov_b32_e32 v11, v0
	v_mov_b32_e32 v12, v0
	v_mov_b32_e32 v13, v0
	v_mov_b32_e32 v14, v0
	v_mov_b32_e32 v15, v0
	v_mov_b32_e32 v24, v0
	v_mov_b32_e32 v25, v0
	v_mov_b32_e32 v26, v0
	v_mov_b32_e32 v27, v0
	v_mov_b32_e32 v28, v0
	v_mov_b32_e32 v29, v0
	v_mov_b32_e32 v30, v0
	v_mov_b32_e32 v31, v0
	v_mov_b32_e32 v40, v0
	v_mov_b32_e32 v41, v0
	v_mov_b32_e32 v42, v0
	v_mov_b32_e32 v43, v0
	v_mov_b32_e32 v44, v0
	v_mov_b32_e32 v45, v0
	v_mov_b32_e32 v46, v0
	v_mov_b32_e32 v47, v0
	v_mov_b32_e32 v56, v0
	v_mov_b32_e32 v57, v0
	v_mov_b32_e32 v58, v0
	v_mov_b32_e32 v59, v0
	v_mov_b32_e32 v60, v0
	v_mov_b32_e32 v61, v0
	v_mov_b32_e32 v62, v0
	v_mov_b32_e32 v63, v0
	v_mov_b32_e32 v64, v0
	v_mov_b32_e32 v65, v0
	v_mov_b32_e32 v66, v0
	v_mov_b32_e32 v67, v0
	v_mov_b32_e32 v68, v0
	v_mov_b32_e32 v69, v0
	v_mov_b32_e32 v70, v0
	v_mov_b32_e32 v71, v0
	v_mov_b32_e32 v80, v0
	v_mov_b32_e32 v81, v0
	v_mov_b32_e32 v82, v0
	v_mov_b32_e32 v83, v0
	v_mov_b32_e32 v84, v0
	v_mov_b32_e32 v85, v0
	v_mov_b32_e32 v86, v0
	v_mov_b32_e32 v87, v0
	v_mov_b32_e32 v96, v0
	v_mov_b32_e32 v97, v0
	v_mov_b32_e32 v98, v0
	v_mov_b32_e32 v99, v0
	v_mov_b32_e32 v100, v0
	v_mov_b32_e32 v101, v0
	v_mov_b32_e32 v102, v0
	v_mov_b32_e32 v103, v0
	v_mov_b32_e32 v112, v0
	v_mov_b32_e32 v113, v0
	v_mov_b32_e32 v114, v0
	v_mov_b32_e32 v115, v0
	v_mov_b32_e32 v116, v0
	v_mov_b32_e32 v117, v0
	v_mov_b32_e32 v118, v0
	v_mov_b32_e32 v119, v0
	v_mov_b32_e32 v72, v0
	v_mov_b32_e32 v73, v0
	v_mov_b32_e32 v74, v0
	v_mov_b32_e32 v75, v0
	v_mov_b32_e32 v76, v0
	v_mov_b32_e32 v77, v0
	v_mov_b32_e32 v78, v0
	v_mov_b32_e32 v79, v0
	v_mov_b32_e32 v88, v0
	v_mov_b32_e32 v89, v0
	v_mov_b32_e32 v90, v0
	v_mov_b32_e32 v91, v0
	v_mov_b32_e32 v92, v0
	v_mov_b32_e32 v93, v0
	v_mov_b32_e32 v94, v0
	v_mov_b32_e32 v95, v0
	v_mov_b32_e32 v104, v0
	v_mov_b32_e32 v105, v0
	v_mov_b32_e32 v106, v0
	v_mov_b32_e32 v107, v0
	v_mov_b32_e32 v108, v0
	v_mov_b32_e32 v109, v0
	v_mov_b32_e32 v110, v0
	v_mov_b32_e32 v111, v0
	v_mov_b32_e32 v120, v0
	v_mov_b32_e32 v121, v0
	v_mov_b32_e32 v122, v0
	v_mov_b32_e32 v123, v0
	v_mov_b32_e32 v124, v0
	v_mov_b32_e32 v125, v0
	v_mov_b32_e32 v126, v0
	v_mov_b32_e32 v127, v0

; template <class Epi, class Sched, bool ALIGN_EPI = false, bool SP2 = false>
; __device__ __forceinline__ void gemm_phase(PG8_LAS unsigned char* lds, const Gemm g, const Sched& S, const Epi& E, const int tid_in) {
;     ...
; #pragma unroll
;         for (int a = 0; a < 2; ++a)
; #pragma unroll
;             for (int b = 0; b < 2; ++b)
; #pragma unroll
;                 for (int m = 0; m < 4; ++m)
; #pragma unroll
;                     for (int n = 0; n < 2; ++n) acc[a][b][m][n] = (f32x4){0.f, 0.f, 0.f, 0.f};
;         cur = nxt; cA = nA; cB = nB; ++ui;
.Lzk_2:
	v_mov_b32_e32 v123, 0
	v_mov_b32_e32 v122, v123
	v_mov_b32_e32 v121, v123
	v_mov_b32_e32 v120, v123
	v_mov_b32_e32 v127, v123
	v_mov_b32_e32 v126, v123
	v_mov_b32_e32 v125, v123
	v_mov_b32_e32 v124, v123
	v_mov_b32_e32 v111, v123
	v_mov_b32_e32 v110, v123
	v_mov_b32_e32 v109, v123
	v_mov_b32_e32 v108, v123
	v_mov_b32_e32 v107, v123
	v_mov_b32_e32 v106, v123
	v_mov_b32_e32 v105, v123
	v_mov_b32_e32 v104, v123
	v_mov_b32_e32 v95, v123
	v_mov_b32_e32 v94, v123
	v_mov_b32_e32 v93, v123
	v_mov_b32_e32 v92, v123
	v_mov_b32_e32 v91, v123
	v_mov_b32_e32 v90, v123
	v_mov_b32_e32 v89, v123
	v_mov_b32_e32 v88, v123
	v_mov_b32_e32 v79, v123
	v_mov_b32_e32 v78, v123
	v_mov_b32_e32 v77, v123
	v_mov_b32_e32 v76, v123
	v_mov_b32_e32 v75, v123
	v_mov_b32_e32 v74, v123
	v_mov_b32_e32 v73, v123
	v_mov_b32_e32 v72, v123
	v_mov_b32_e32 v119, v123
	v_mov_b32_e32 v118, v123
	v_mov_b32_e32 v117, v123
	v_mov_b32_e32 v116, v123
	v_mov_b32_e32 v115, v123
	v_mov_b32_e32 v114, v123
	v_mov_b32_e32 v113, v123
	v_mov_b32_e32 v112, v123
	v_mov_b32_e32 v103, v123
	v_mov_b32_e32 v102, v123
	v_mov_b32_e32 v101, v123
	v_mov_b32_e32 v100, v123
	v_mov_b32_e32 v99, v123
	v_mov_b32_e32 v98, v123
	v_mov_b32_e32 v97, v123
	v_mov_b32_e32 v96, v123
	v_mov_b32_e32 v87, v123
	v_mov_b32_e32 v86, v123
	v_mov_b32_e32 v85, v123
	v_mov_b32_e32 v84, v123
	v_mov_b32_e32 v83, v123
	v_mov_b32_e32 v82, v123
	v_mov_b32_e32 v81, v123
	v_mov_b32_e32 v80, v123
	v_mov_b32_e32 v71, v123
	v_mov_b32_e32 v70, v123
	v_mov_b32_e32 v69, v123
	v_mov_b32_e32 v68, v123
	v_mov_b32_e32 v67, v123
	v_mov_b32_e32 v66, v123
	v_mov_b32_e32 v65, v123
	v_mov_b32_e32 v64, v123
	v_mov_b32_e32 v63, v123
	v_mov_b32_e32 v62, v123
	v_mov_b32_e32 v61, v123
	v_mov_b32_e32 v60, v123
	v_mov_b32_e32 v59, v123
	v_mov_b32_e32 v58, v123
	v_mov_b32_e32 v57, v123
	v_mov_b32_e32 v56, v123
	v_mov_b32_e32 v47, v123
	v_mov_b32_e32 v46, v123
	v_mov_b32_e32 v45, v123
	v_mov_b32_e32 v44, v123
	v_mov_b32_e32 v43, v123
	v_mov_b32_e32 v42, v123
	v_mov_b32_e32 v41, v123
	v_mov_b32_e32 v40, v123
	v_mov_b32_e32 v31, v123
	v_mov_b32_e32 v30, v123
	v_mov_b32_e32 v29, v123
	v_mov_b32_e32 v28, v123
	v_mov_b32_e32 v27, v123
	v_mov_b32_e32 v26, v123
	v_mov_b32_e32 v25, v123
	v_mov_b32_e32 v24, v123
	v_mov_b32_e32 v15, v123
	v_mov_b32_e32 v14, v123
	v_mov_b32_e32 v13, v123
	v_mov_b32_e32 v12, v123
	v_mov_b32_e32 v11, v123
	v_mov_b32_e32 v10, v123
	v_mov_b32_e32 v9, v123
	v_mov_b32_e32 v8, v123
	v_mov_b32_e32 v55, v123
	v_mov_b32_e32 v54, v123
	v_mov_b32_e32 v53, v123
	v_mov_b32_e32 v52, v123
	v_mov_b32_e32 v51, v123
	v_mov_b32_e32 v50, v123
	v_mov_b32_e32 v49, v123
	v_mov_b32_e32 v48, v123
	v_mov_b32_e32 v39, v123
	v_mov_b32_e32 v38, v123
	v_mov_b32_e32 v37, v123
	v_mov_b32_e32 v36, v123
	v_mov_b32_e32 v35, v123
	v_mov_b32_e32 v34, v123
	v_mov_b32_e32 v33, v123
	v_mov_b32_e32 v32, v123
	v_mov_b32_e32 v23, v123
	v_mov_b32_e32 v22, v123
	v_mov_b32_e32 v21, v123
	v_mov_b32_e32 v20, v123
	v_mov_b32_e32 v19, v123
	v_mov_b32_e32 v18, v123
	v_mov_b32_e32 v17, v123
	v_mov_b32_e32 v16, v123
	v_mov_b32_e32 v7, v123
	v_mov_b32_e32 v6, v123
	v_mov_b32_e32 v5, v123
	v_mov_b32_e32 v4, v123
	v_mov_b32_e32 v3, v123
	v_mov_b32_e32 v2, v123
	v_mov_b32_e32 v1, v123
	v_mov_b32_e32 v0, v123
	s_branch .LBB0_289

; template <class Epi, class Sched, bool ALIGN_EPI = false, bool SP2 = false>
; __device__ __forceinline__ void gemm_phase(PG8_LAS unsigned char* lds, const Gemm g, const Sched& S, const Epi& E, const int tid_in) {
;     ...
;         const bool has_next = S.next(ui + 1, nxt);
;         const char* nA = has_next ? (const char*)g.A + (size_t)nxt.pm * tstep : cA; const char* nB = has_next ? (const char*)g.Bt + (size_t)nxt.pn * tstep : cB;
;         for (int t = 0; t < nt; t += 2) {
;             const bool last = (t == nt - 2);
;             const char* a1 = cA + (size_t)(t + 1) * kstep;
;             const char* a2 = last ? nA : cA + (size_t)(t + 2) * kstep; const char* b2 = last ? nB : cB + (size_t)(t + 2) * kstep;
;             const char* a3 = a2 + kstep; const char* b3 = b2 + kstep;
;     ...
; #pragma unroll
;         for (int a = 0; a < 2; ++a)
; #pragma unroll
;             for (int b = 0; b < 2; ++b)
; #pragma unroll
;                 for (int m = 0; m < 4; ++m)
; #pragma unroll
;                     for (int n = 0; n < 2; ++n) acc[a][b][m][n] = (f32x4){0.f, 0.f, 0.f, 0.f};
;         cur = nxt; cA = nA; cB = nB; ++ui;
.LBB0_286:
	s_ashr_i32 s17, s16, 31
	s_lshl_b64 s[18:19], s[16:17], 21
	s_add_u32 s18, s34, s18
	s_addc_u32 s19, s35, s19
	s_ashr_i32 s15, s14, 31
	s_lshl_b64 s[20:21], s[14:15], 21
	s_add_u32 s20, s36, s20
	s_addc_u32 s21, s37, s21
	s_andn2_b64 vcc, exec, s[6:7]
	s_cbranch_vccnz .Lzk_2
	s_and_b64 s[26:27], s[0:1], exec
	s_cselect_b32 s11, s19, s23
	s_cselect_b32 s13, s18, s22
	s_cselect_b32 s15, s21, s25
	s_cselect_b32 s17, s20, s24
	s_add_u32 s22, s22, 0x100080
	s_addc_u32 s23, s23, 0
	s_add_u32 s54, s24, 0x100
	v_mov_b32_e32 v0, 0
	s_addc_u32 s55, s25, 0
	s_mov_b32 s24, 0
	v_mov_b32_e32 v1, v0
	v_mov_b32_e32 v2, v0
	v_mov_b32_e32 v3, v0
	v_mov_b32_e32 v4, v0
	v_mov_b32_e32 v5, v0
	v_mov_b32_e32 v6, v0
	v_mov_b32_e32 v7, v0
	v_mov_b32_e32 v16, v0
	v_mov_b32_e32 v17, v0
	v_mov_b32_e32 v18, v0
	v_mov_b32_e32 v19, v0
	v_mov_b32_e32 v20, v0
	v_mov_b32_e32 v21, v0
	v_mov_b32_e32 v22, v0
	v_mov_b32_e32 v23, v0
	v_mov_b32_e32 v32, v0
	v_mov_b32_e32 v33, v0
	v_mov_b32_e32 v34, v0
	v_mov_b32_e32 v35, v0
	v_mov_b32_e32 v36, v0
	v_mov_b32_e32 v37, v0
	v_mov_b32_e32 v38, v0
	v_mov_b32_e32 v39, v0
	v_mov_b32_e32 v48, v0
	v_mov_b32_e32 v49, v0
	v_mov_b32_e32 v50, v0
	v_mov_b32_e32 v51, v0
	v_mov_b32_e32 v52, v0
	v_mov_b32_e32 v53, v0
	v_mov_b32_e32 v54, v0
	v_mov_b32_e32 v55, v0
	v_mov_b32_e32 v8, v0
	v_mov_b32_e32 v9, v0
	v_mov_b32_e32 v10, v0
	v_mov_b32_e32 v11, v0
	v_mov_b32_e32 v12, v0
	v_mov_b32_e32 v13, v0
	v_mov_b32_e32 v14, v0
	v_mov_b32_e32 v15, v0
	v_mov_b32_e32 v24, v0
	v_mov_b32_e32 v25, v0
	v_mov_b32_e32 v26, v0
	v_mov_b32_e32 v27, v0
	v_mov_b32_e32 v28, v0
	v_mov_b32_e32 v29, v0
	v_mov_b32_e32 v30, v0
	v_mov_b32_e32 v31, v0
	v_mov_b32_e32 v40, v0
	v_mov_b32_e32 v41, v0
	v_mov_b32_e32 v42, v0
	v_mov_b32_e32 v43, v0
	v_mov_b32_e32 v44, v0
	v_mov_b32_e32 v45, v0
	v_mov_b32_e32 v46, v0
	v_mov_b32_e32 v47, v0
	v_mov_b32_e32 v56, v0
	v_mov_b32_e32 v57, v0
	v_mov_b32_e32 v58, v0
	v_mov_b32_e32 v59, v0
	v_mov_b32_e32 v60, v0
	v_mov_b32_e32 v61, v0
	v_mov_b32_e32 v62, v0
	v_mov_b32_e32 v63, v0
	v_mov_b32_e32 v64, v0
	v_mov_b32_e32 v65, v0
	v_mov_b32_e32 v66, v0
	v_mov_b32_e32 v67, v0
	v_mov_b32_e32 v68, v0
	v_mov_b32_e32 v69, v0
	v_mov_b32_e32 v70, v0
	v_mov_b32_e32 v71, v0
	v_mov_b32_e32 v80, v0
	v_mov_b32_e32 v81, v0
	v_mov_b32_e32 v82, v0
	v_mov_b32_e32 v83, v0
	v_mov_b32_e32 v84, v0
	v_mov_b32_e32 v85, v0
	v_mov_b32_e32 v86, v0
	v_mov_b32_e32 v87, v0
	v_mov_b32_e32 v96, v0
	v_mov_b32_e32 v97, v0
	v_mov_b32_e32 v98, v0
	v_mov_b32_e32 v99, v0
	v_mov_b32_e32 v100, v0
	v_mov_b32_e32 v101, v0
	v_mov_b32_e32 v102, v0
	v_mov_b32_e32 v103, v0
	v_mov_b32_e32 v112, v0
	v_mov_b32_e32 v113, v0
	v_mov_b32_e32 v114, v0
	v_mov_b32_e32 v115, v0
	v_mov_b32_e32 v116, v0
	v_mov_b32_e32 v117, v0
	v_mov_b32_e32 v118, v0
	v_mov_b32_e32 v119, v0
	v_mov_b32_e32 v72, v0
	v_mov_b32_e32 v73, v0
	v_mov_b32_e32 v74, v0
	v_mov_b32_e32 v75, v0
	v_mov_b32_e32 v76, v0
	v_mov_b32_e32 v77, v0
	v_mov_b32_e32 v78, v0
	v_mov_b32_e32 v79, v0
	v_mov_b32_e32 v88, v0
	v_mov_b32_e32 v89, v0
	v_mov_b32_e32 v90, v0
	v_mov_b32_e32 v91, v0
	v_mov_b32_e32 v92, v0
	v_mov_b32_e32 v93, v0
	v_mov_b32_e32 v94, v0
	v_mov_b32_e32 v95, v0
	v_mov_b32_e32 v104, v0
	v_mov_b32_e32 v105, v0
	v_mov_b32_e32 v106, v0
	v_mov_b32_e32 v107, v0
	v_mov_b32_e32 v108, v0
	v_mov_b32_e32 v109, v0
	v_mov_b32_e32 v110, v0
	v_mov_b32_e32 v111, v0
	v_mov_b32_e32 v124, v0
	v_mov_b32_e32 v125, v0
	v_mov_b32_e32 v126, v0
	v_mov_b32_e32 v127, v0
	v_mov_b32_e32 v120, v0
	v_mov_b32_e32 v121, v0
	v_mov_b32_e32 v122, v0
	v_mov_b32_e32 v123, v0

; template <class Epi, class Sched, bool ALIGN_EPI = false, bool SP2 = false>
; __device__ __forceinline__ void gemm_phase(PG8_LAS unsigned char* lds, const Gemm g, const Sched& S, const Epi& E, const int tid_in) {
;     ...
;         for (int t = 0; t < nt; t += 2) {
;             const bool last = (t == nt - 2);
;             const char* a1 = cA + (size_t)(t + 1) * kstep;
;             const char* a2 = last ? nA : cA + (size_t)(t + 2) * kstep; const char* b2 = last ? nB : cB + (size_t)(t + 2) * kstep;
;             const char* a3 = a2 + kstep; const char* b3 = b2 + kstep;
;     ...
; #pragma unroll
;         for (int a = 0; a < 2; ++a)
; #pragma unroll
;             for (int b = 0; b < 2; ++b)
; #pragma unroll
;                 for (int m = 0; m < 4; ++m)
; #pragma unroll
;                     for (int n = 0; n < 2; ++n) acc[a][b][m][n] = (f32x4){0.f, 0.f, 0.f, 0.f};
;         cur = nxt; cA = nA; cB = nB; ++ui;
.LBB0_327:
	s_andn2_b64 vcc, exec, s[20:21]
	s_cbranch_vccnz .Lzk_3
	s_add_u32 s26, s26, 0x80
	s_addc_u32 s27, s27, 0
	s_add_u32 s59, s28, 0x100
	v_mov_b32_e32 v0, 0
	s_addc_u32 s60, s29, 0
	s_mov_b32 s28, 0
	v_mov_b32_e32 v1, v0
	v_mov_b32_e32 v2, v0
	v_mov_b32_e32 v3, v0
	v_mov_b32_e32 v4, v0
	v_mov_b32_e32 v5, v0
	v_mov_b32_e32 v6, v0
	v_mov_b32_e32 v7, v0
	v_mov_b32_e32 v16, v0
	v_mov_b32_e32 v17, v0
	v_mov_b32_e32 v18, v0
	v_mov_b32_e32 v19, v0
	v_mov_b32_e32 v20, v0
	v_mov_b32_e32 v21, v0
	v_mov_b32_e32 v22, v0
	v_mov_b32_e32 v23, v0
	v_mov_b32_e32 v32, v0
	v_mov_b32_e32 v33, v0
	v_mov_b32_e32 v34, v0
	v_mov_b32_e32 v35, v0
	v_mov_b32_e32 v36, v0
	v_mov_b32_e32 v37, v0
	v_mov_b32_e32 v38, v0
	v_mov_b32_e32 v39, v0
	v_mov_b32_e32 v48, v0
	v_mov_b32_e32 v49, v0
	v_mov_b32_e32 v50, v0
	v_mov_b32_e32 v51, v0
	v_mov_b32_e32 v52, v0
	v_mov_b32_e32 v53, v0
	v_mov_b32_e32 v54, v0
	v_mov_b32_e32 v55, v0
	v_mov_b32_e32 v8, v0
	v_mov_b32_e32 v9, v0
	v_mov_b32_e32 v10, v0
	v_mov_b32_e32 v11, v0
	v_mov_b32_e32 v12, v0
	v_mov_b32_e32 v13, v0
	v_mov_b32_e32 v14, v0
	v_mov_b32_e32 v15, v0
	v_mov_b32_e32 v24, v0
	v_mov_b32_e32 v25, v0
	v_mov_b32_e32 v26, v0
	v_mov_b32_e32 v27, v0
	v_mov_b32_e32 v28, v0
	v_mov_b32_e32 v29, v0
	v_mov_b32_e32 v30, v0
	v_mov_b32_e32 v31, v0
	v_mov_b32_e32 v40, v0
	v_mov_b32_e32 v41, v0
	v_mov_b32_e32 v42, v0
	v_mov_b32_e32 v43, v0
	v_mov_b32_e32 v44, v0
	v_mov_b32_e32 v45, v0
	v_mov_b32_e32 v46, v0
	v_mov_b32_e32 v47, v0
	v_mov_b32_e32 v56, v0
	v_mov_b32_e32 v57, v0
	v_mov_b32_e32 v58, v0
	v_mov_b32_e32 v59, v0
	v_mov_b32_e32 v60, v0
	v_mov_b32_e32 v61, v0
	v_mov_b32_e32 v62, v0
	v_mov_b32_e32 v63, v0
	v_mov_b32_e32 v64, v0
	v_mov_b32_e32 v65, v0
	v_mov_b32_e32 v66, v0
	v_mov_b32_e32 v67, v0
	v_mov_b32_e32 v68, v0
	v_mov_b32_e32 v69, v0
	v_mov_b32_e32 v70, v0
	v_mov_b32_e32 v71, v0
	v_mov_b32_e32 v80, v0
	v_mov_b32_e32 v81, v0
	v_mov_b32_e32 v82, v0
	v_mov_b32_e32 v83, v0
	v_mov_b32_e32 v84, v0
	v_mov_b32_e32 v85, v0
	v_mov_b32_e32 v86, v0
	v_mov_b32_e32 v87, v0
	v_mov_b32_e32 v96, v0
	v_mov_b32_e32 v97, v0
	v_mov_b32_e32 v98, v0
	v_mov_b32_e32 v99, v0
	v_mov_b32_e32 v100, v0
	v_mov_b32_e32 v101, v0
	v_mov_b32_e32 v102, v0
	v_mov_b32_e32 v103, v0
	v_mov_b32_e32 v112, v0
	v_mov_b32_e32 v113, v0
	v_mov_b32_e32 v114, v0
	v_mov_b32_e32 v115, v0
	v_mov_b32_e32 v116, v0
	v_mov_b32_e32 v117, v0
	v_mov_b32_e32 v118, v0
	v_mov_b32_e32 v119, v0
	v_mov_b32_e32 v72, v0
	v_mov_b32_e32 v73, v0
	v_mov_b32_e32 v74, v0
	v_mov_b32_e32 v75, v0
	v_mov_b32_e32 v76, v0
	v_mov_b32_e32 v77, v0
	v_mov_b32_e32 v78, v0
	v_mov_b32_e32 v79, v0
	v_mov_b32_e32 v88, v0
	v_mov_b32_e32 v89, v0
	v_mov_b32_e32 v90, v0
	v_mov_b32_e32 v91, v0
	v_mov_b32_e32 v92, v0
	v_mov_b32_e32 v93, v0
	v_mov_b32_e32 v94, v0
	v_mov_b32_e32 v95, v0
	v_mov_b32_e32 v104, v0
	v_mov_b32_e32 v105, v0
	v_mov_b32_e32 v106, v0
	v_mov_b32_e32 v107, v0
	v_mov_b32_e32 v108, v0
	v_mov_b32_e32 v109, v0
	v_mov_b32_e32 v110, v0
	v_mov_b32_e32 v111, v0
	v_mov_b32_e32 v120, v0
	v_mov_b32_e32 v121, v0
	v_mov_b32_e32 v122, v0
	v_mov_b32_e32 v123, v0
	v_mov_b32_e32 v124, v0
	v_mov_b32_e32 v125, v0
	v_mov_b32_e32 v126, v0
	v_mov_b32_e32 v127, v0

; template <class Epi, class Sched, bool ALIGN_EPI = false, bool SP2 = false>
; __device__ __forceinline__ void gemm_phase(PG8_LAS unsigned char* lds, const Gemm g, const Sched& S, const Epi& E, const int tid_in) {
;     ...
;         for (int t = 0; t < nt; t += 2) {
;             const bool last = (t == nt - 2);
;             const char* a1 = cA + (size_t)(t + 1) * kstep;
;             const char* a2 = last ? nA : cA + (size_t)(t + 2) * kstep; const char* b2 = last ? nB : cB + (size_t)(t + 2) * kstep;
;             const char* a3 = a2 + kstep; const char* b3 = b2 + kstep;
;     ...
; #pragma unroll
;         for (int a = 0; a < 2; ++a)
; #pragma unroll
;             for (int b = 0; b < 2; ++b)
; #pragma unroll
;                 for (int m = 0; m < 4; ++m)
; #pragma unroll
;                     for (int n = 0; n < 2; ++n) acc[a][b][m][n] = (f32x4){0.f, 0.f, 0.f, 0.f};
;         cur = nxt; cA = nA; cB = nB; ++ui;
.LBB0_377:
	s_andn2_b64 vcc, exec, s[18:19]
	s_cbranch_vccnz .Lzk_4
	s_add_u32 s24, s24, 0x80
	s_addc_u32 s25, s25, 0
	s_add_u32 s55, s26, 0x100
	v_mov_b32_e32 v0, 0
	s_addc_u32 s56, s27, 0
	s_mov_b32 s26, 0
	v_mov_b32_e32 v1, v0
	v_mov_b32_e32 v2, v0
	v_mov_b32_e32 v3, v0
	v_mov_b32_e32 v4, v0
	v_mov_b32_e32 v5, v0
	v_mov_b32_e32 v6, v0
	v_mov_b32_e32 v7, v0
	v_mov_b32_e32 v16, v0
	v_mov_b32_e32 v17, v0
	v_mov_b32_e32 v18, v0
	v_mov_b32_e32 v19, v0
	v_mov_b32_e32 v20, v0
	v_mov_b32_e32 v21, v0
	v_mov_b32_e32 v22, v0
	v_mov_b32_e32 v23, v0
	v_mov_b32_e32 v32, v0
	v_mov_b32_e32 v33, v0
	v_mov_b32_e32 v34, v0
	v_mov_b32_e32 v35, v0
	v_mov_b32_e32 v36, v0
	v_mov_b32_e32 v37, v0
	v_mov_b32_e32 v38, v0
	v_mov_b32_e32 v39, v0
	v_mov_b32_e32 v48, v0
	v_mov_b32_e32 v49, v0
	v_mov_b32_e32 v50, v0
	v_mov_b32_e32 v51, v0
	v_mov_b32_e32 v52, v0
	v_mov_b32_e32 v53, v0
	v_mov_b32_e32 v54, v0
	v_mov_b32_e32 v55, v0
	v_mov_b32_e32 v8, v0
	v_mov_b32_e32 v9, v0
	v_mov_b32_e32 v10, v0
	v_mov_b32_e32 v11, v0
	v_mov_b32_e32 v12, v0
	v_mov_b32_e32 v13, v0
	v_mov_b32_e32 v14, v0
	v_mov_b32_e32 v15, v0
	v_mov_b32_e32 v24, v0
	v_mov_b32_e32 v25, v0
	v_mov_b32_e32 v26, v0
	v_mov_b32_e32 v27, v0
	v_mov_b32_e32 v28, v0
	v_mov_b32_e32 v29, v0
	v_mov_b32_e32 v30, v0
	v_mov_b32_e32 v31, v0
	v_mov_b32_e32 v40, v0
	v_mov_b32_e32 v41, v0
	v_mov_b32_e32 v42, v0
	v_mov_b32_e32 v43, v0
	v_mov_b32_e32 v44, v0
	v_mov_b32_e32 v45, v0
	v_mov_b32_e32 v46, v0
	v_mov_b32_e32 v47, v0
	v_mov_b32_e32 v56, v0
	v_mov_b32_e32 v57, v0
	v_mov_b32_e32 v58, v0
	v_mov_b32_e32 v59, v0
	v_mov_b32_e32 v60, v0
	v_mov_b32_e32 v61, v0
	v_mov_b32_e32 v62, v0
	v_mov_b32_e32 v63, v0
	v_mov_b32_e32 v64, v0
	v_mov_b32_e32 v65, v0
	v_mov_b32_e32 v66, v0
	v_mov_b32_e32 v67, v0
	v_mov_b32_e32 v68, v0
	v_mov_b32_e32 v69, v0
	v_mov_b32_e32 v70, v0
	v_mov_b32_e32 v71, v0
	v_mov_b32_e32 v80, v0
	v_mov_b32_e32 v81, v0
	v_mov_b32_e32 v82, v0
	v_mov_b32_e32 v83, v0
	v_mov_b32_e32 v84, v0
	v_mov_b32_e32 v85, v0
	v_mov_b32_e32 v86, v0
	v_mov_b32_e32 v87, v0
	v_mov_b32_e32 v96, v0
	v_mov_b32_e32 v97, v0
	v_mov_b32_e32 v98, v0
	v_mov_b32_e32 v99, v0
	v_mov_b32_e32 v100, v0
	v_mov_b32_e32 v101, v0
	v_mov_b32_e32 v102, v0
	v_mov_b32_e32 v103, v0
	v_mov_b32_e32 v112, v0
	v_mov_b32_e32 v113, v0
	v_mov_b32_e32 v114, v0
	v_mov_b32_e32 v115, v0
	v_mov_b32_e32 v116, v0
	v_mov_b32_e32 v117, v0
	v_mov_b32_e32 v118, v0
	v_mov_b32_e32 v119, v0
	v_mov_b32_e32 v72, v0
	v_mov_b32_e32 v73, v0
	v_mov_b32_e32 v74, v0
	v_mov_b32_e32 v75, v0
	v_mov_b32_e32 v76, v0
	v_mov_b32_e32 v77, v0
	v_mov_b32_e32 v78, v0
	v_mov_b32_e32 v79, v0
	v_mov_b32_e32 v88, v0
	v_mov_b32_e32 v89, v0
	v_mov_b32_e32 v90, v0
	v_mov_b32_e32 v91, v0
	v_mov_b32_e32 v92, v0
	v_mov_b32_e32 v93, v0
	v_mov_b32_e32 v94, v0
	v_mov_b32_e32 v95, v0
	v_mov_b32_e32 v104, v0
	v_mov_b32_e32 v105, v0
	v_mov_b32_e32 v106, v0
	v_mov_b32_e32 v107, v0
	v_mov_b32_e32 v108, v0
	v_mov_b32_e32 v109, v0
	v_mov_b32_e32 v110, v0
	v_mov_b32_e32 v111, v0
	v_mov_b32_e32 v120, v0
	v_mov_b32_e32 v121, v0
	v_mov_b32_e32 v122, v0
	v_mov_b32_e32 v123, v0
	v_mov_b32_e32 v124, v0
	v_mov_b32_e32 v125, v0
	v_mov_b32_e32 v126, v0
	v_mov_b32_e32 v127, v0

; template <class Epi, class Sched, bool ALIGN_EPI = false, bool SP2 = false>
; __device__ __forceinline__ void gemm_phase(PG8_LAS unsigned char* lds, const Gemm g, const Sched& S, const Epi& E, const int tid_in) {
;     ...
;         for (int t = 0; t < nt; t += 2) {
;             const bool last = (t == nt - 2);
;             const char* a1 = cA + (size_t)(t + 1) * kstep;
;             const char* a2 = last ? nA : cA + (size_t)(t + 2) * kstep; const char* b2 = last ? nB : cB + (size_t)(t + 2) * kstep;
;             const char* a3 = a2 + kstep; const char* b3 = b2 + kstep;
;     ...
; #pragma unroll
;         for (int a = 0; a < 2; ++a)
; #pragma unroll
;             for (int b = 0; b < 2; ++b)
; #pragma unroll
;                 for (int m = 0; m < 4; ++m)
; #pragma unroll
;                     for (int n = 0; n < 2; ++n) acc[a][b][m][n] = (f32x4){0.f, 0.f, 0.f, 0.f};
;         cur = nxt; cA = nA; cB = nB; ++ui;
.LBB0_487:
	s_andn2_b64 vcc, exec, s[14:15]
	s_cbranch_vccnz .Lzk_6
	s_add_u32 s20, s20, 0x80
	s_addc_u32 s21, s21, 0
	s_add_u32 s49, s22, 0x100
	v_mov_b32_e32 v0, 0
	s_addc_u32 s50, s23, 0
	s_mov_b32 s22, 0
	v_mov_b32_e32 v1, v0
	v_mov_b32_e32 v2, v0
	v_mov_b32_e32 v3, v0
	v_mov_b32_e32 v4, v0
	v_mov_b32_e32 v5, v0
	v_mov_b32_e32 v6, v0
	v_mov_b32_e32 v7, v0
	v_mov_b32_e32 v16, v0
	v_mov_b32_e32 v17, v0
	v_mov_b32_e32 v18, v0
	v_mov_b32_e32 v19, v0
	v_mov_b32_e32 v20, v0
	v_mov_b32_e32 v21, v0
	v_mov_b32_e32 v22, v0
	v_mov_b32_e32 v23, v0
	v_mov_b32_e32 v32, v0
	v_mov_b32_e32 v33, v0
	v_mov_b32_e32 v34, v0
	v_mov_b32_e32 v35, v0
	v_mov_b32_e32 v36, v0
	v_mov_b32_e32 v37, v0
	v_mov_b32_e32 v38, v0
	v_mov_b32_e32 v39, v0
	v_mov_b32_e32 v48, v0
	v_mov_b32_e32 v49, v0
	v_mov_b32_e32 v50, v0
	v_mov_b32_e32 v51, v0
	v_mov_b32_e32 v52, v0
	v_mov_b32_e32 v53, v0
	v_mov_b32_e32 v54, v0
	v_mov_b32_e32 v55, v0
	v_mov_b32_e32 v8, v0
	v_mov_b32_e32 v9, v0
	v_mov_b32_e32 v10, v0
	v_mov_b32_e32 v11, v0
	v_mov_b32_e32 v12, v0
	v_mov_b32_e32 v13, v0
	v_mov_b32_e32 v14, v0
	v_mov_b32_e32 v15, v0
	v_mov_b32_e32 v24, v0
	v_mov_b32_e32 v25, v0
	v_mov_b32_e32 v26, v0
	v_mov_b32_e32 v27, v0
	v_mov_b32_e32 v28, v0
	v_mov_b32_e32 v29, v0
	v_mov_b32_e32 v30, v0
	v_mov_b32_e32 v31, v0
	v_mov_b32_e32 v40, v0
	v_mov_b32_e32 v41, v0
	v_mov_b32_e32 v42, v0
	v_mov_b32_e32 v43, v0
	v_mov_b32_e32 v44, v0
	v_mov_b32_e32 v45, v0
	v_mov_b32_e32 v46, v0
	v_mov_b32_e32 v47, v0
	v_mov_b32_e32 v56, v0
	v_mov_b32_e32 v57, v0
	v_mov_b32_e32 v58, v0
	v_mov_b32_e32 v59, v0
	v_mov_b32_e32 v60, v0
	v_mov_b32_e32 v61, v0
	v_mov_b32_e32 v62, v0
	v_mov_b32_e32 v63, v0
	v_mov_b32_e32 v64, v0
	v_mov_b32_e32 v65, v0
	v_mov_b32_e32 v66, v0
	v_mov_b32_e32 v67, v0
	v_mov_b32_e32 v68, v0
	v_mov_b32_e32 v69, v0
	v_mov_b32_e32 v70, v0
	v_mov_b32_e32 v71, v0
	v_mov_b32_e32 v80, v0
	v_mov_b32_e32 v81, v0
	v_mov_b32_e32 v82, v0
	v_mov_b32_e32 v83, v0
	v_mov_b32_e32 v84, v0
	v_mov_b32_e32 v85, v0
	v_mov_b32_e32 v86, v0
	v_mov_b32_e32 v87, v0
	v_mov_b32_e32 v96, v0
	v_mov_b32_e32 v97, v0
	v_mov_b32_e32 v98, v0
	v_mov_b32_e32 v99, v0
	v_mov_b32_e32 v100, v0
	v_mov_b32_e32 v101, v0
	v_mov_b32_e32 v102, v0
	v_mov_b32_e32 v103, v0
	v_mov_b32_e32 v112, v0
	v_mov_b32_e32 v113, v0
	v_mov_b32_e32 v114, v0
	v_mov_b32_e32 v115, v0
	v_mov_b32_e32 v116, v0
	v_mov_b32_e32 v117, v0
	v_mov_b32_e32 v118, v0
	v_mov_b32_e32 v119, v0
	v_mov_b32_e32 v72, v0
	v_mov_b32_e32 v73, v0
	v_mov_b32_e32 v74, v0
	v_mov_b32_e32 v75, v0
	v_mov_b32_e32 v76, v0
	v_mov_b32_e32 v77, v0
	v_mov_b32_e32 v78, v0
	v_mov_b32_e32 v79, v0
	v_mov_b32_e32 v88, v0
	v_mov_b32_e32 v89, v0
	v_mov_b32_e32 v90, v0
	v_mov_b32_e32 v91, v0
	v_mov_b32_e32 v92, v0
	v_mov_b32_e32 v93, v0
	v_mov_b32_e32 v94, v0
	v_mov_b32_e32 v95, v0
	v_mov_b32_e32 v104, v0
	v_mov_b32_e32 v105, v0
	v_mov_b32_e32 v106, v0
	v_mov_b32_e32 v107, v0
	v_mov_b32_e32 v108, v0
	v_mov_b32_e32 v109, v0
	v_mov_b32_e32 v110, v0
	v_mov_b32_e32 v111, v0
	v_mov_b32_e32 v124, v0
	v_mov_b32_e32 v125, v0
	v_mov_b32_e32 v126, v0
	v_mov_b32_e32 v127, v0
	v_mov_b32_e32 v120, v0
	v_mov_b32_e32 v121, v0
	v_mov_b32_e32 v122, v0
	v_mov_b32_e32 v123, v0

; template <class Epi, class Sched, bool ALIGN_EPI = false, bool SP2 = false>
; __device__ __forceinline__ void gemm_phase(PG8_LAS unsigned char* lds, const Gemm g, const Sched& S, const Epi& E, const int tid_in) {
;     ...
;         for (int t = 0; t < nt; t += 2) {
;             const bool last = (t == nt - 2);
;             const char* a1 = cA + (size_t)(t + 1) * kstep;
;             const char* a2 = last ? nA : cA + (size_t)(t + 2) * kstep; const char* b2 = last ? nB : cB + (size_t)(t + 2) * kstep;
;             const char* a3 = a2 + kstep; const char* b3 = b2 + kstep;
;     ...
; #pragma unroll
;         for (int a = 0; a < 2; ++a)
; #pragma unroll
;             for (int b = 0; b < 2; ++b)
; #pragma unroll
;                 for (int m = 0; m < 4; ++m)
; #pragma unroll
;                     for (int n = 0; n < 2; ++n) acc[a][b][m][n] = (f32x4){0.f, 0.f, 0.f, 0.f};
;         cur = nxt; cA = nA; cB = nB; ++ui;
.LBB0_680:
	s_andn2_b64 vcc, exec, s[18:19]
	s_cbranch_vccnz .Lzk_7
	s_add_u32 s22, s22, 0x80
	s_addc_u32 s23, s23, 0
	s_add_u32 s56, s28, 0x100
	v_mov_b32_e32 v0, 0
	s_addc_u32 s57, s29, 0
	s_mov_b32 s28, 0
	v_mov_b32_e32 v1, v0
	v_mov_b32_e32 v2, v0
	v_mov_b32_e32 v3, v0
	v_mov_b32_e32 v4, v0
	v_mov_b32_e32 v5, v0
	v_mov_b32_e32 v6, v0
	v_mov_b32_e32 v7, v0
	v_mov_b32_e32 v16, v0
	v_mov_b32_e32 v17, v0
	v_mov_b32_e32 v18, v0
	v_mov_b32_e32 v19, v0
	v_mov_b32_e32 v20, v0
	v_mov_b32_e32 v21, v0
	v_mov_b32_e32 v22, v0
	v_mov_b32_e32 v23, v0
	v_mov_b32_e32 v32, v0
	v_mov_b32_e32 v33, v0
	v_mov_b32_e32 v34, v0
	v_mov_b32_e32 v35, v0
	v_mov_b32_e32 v36, v0
	v_mov_b32_e32 v37, v0
	v_mov_b32_e32 v38, v0
	v_mov_b32_e32 v39, v0
	v_mov_b32_e32 v48, v0
	v_mov_b32_e32 v49, v0
	v_mov_b32_e32 v50, v0
	v_mov_b32_e32 v51, v0
	v_mov_b32_e32 v52, v0
	v_mov_b32_e32 v53, v0
	v_mov_b32_e32 v54, v0
	v_mov_b32_e32 v55, v0
	v_mov_b32_e32 v8, v0
	v_mov_b32_e32 v9, v0
	v_mov_b32_e32 v10, v0
	v_mov_b32_e32 v11, v0
	v_mov_b32_e32 v12, v0
	v_mov_b32_e32 v13, v0
	v_mov_b32_e32 v14, v0
	v_mov_b32_e32 v15, v0
	v_mov_b32_e32 v24, v0
	v_mov_b32_e32 v25, v0
	v_mov_b32_e32 v26, v0
	v_mov_b32_e32 v27, v0
	v_mov_b32_e32 v28, v0
	v_mov_b32_e32 v29, v0
	v_mov_b32_e32 v30, v0
	v_mov_b32_e32 v31, v0
	v_mov_b32_e32 v40, v0
	v_mov_b32_e32 v41, v0
	v_mov_b32_e32 v42, v0
	v_mov_b32_e32 v43, v0
	v_mov_b32_e32 v44, v0
	v_mov_b32_e32 v45, v0
	v_mov_b32_e32 v46, v0
	v_mov_b32_e32 v47, v0
	v_mov_b32_e32 v56, v0
	v_mov_b32_e32 v57, v0
	v_mov_b32_e32 v58, v0
	v_mov_b32_e32 v59, v0
	v_mov_b32_e32 v60, v0
	v_mov_b32_e32 v61, v0
	v_mov_b32_e32 v62, v0
	v_mov_b32_e32 v63, v0
	v_mov_b32_e32 v64, v0
	v_mov_b32_e32 v65, v0
	v_mov_b32_e32 v66, v0
	v_mov_b32_e32 v67, v0
	v_mov_b32_e32 v68, v0
	v_mov_b32_e32 v69, v0
	v_mov_b32_e32 v70, v0
	v_mov_b32_e32 v71, v0
	v_mov_b32_e32 v80, v0
	v_mov_b32_e32 v81, v0
	v_mov_b32_e32 v82, v0
	v_mov_b32_e32 v83, v0
	v_mov_b32_e32 v84, v0
	v_mov_b32_e32 v85, v0
	v_mov_b32_e32 v86, v0
	v_mov_b32_e32 v87, v0
	v_mov_b32_e32 v96, v0
	v_mov_b32_e32 v97, v0
	v_mov_b32_e32 v98, v0
	v_mov_b32_e32 v99, v0
	v_mov_b32_e32 v100, v0
	v_mov_b32_e32 v101, v0
	v_mov_b32_e32 v102, v0
	v_mov_b32_e32 v103, v0
	v_mov_b32_e32 v112, v0
	v_mov_b32_e32 v113, v0
	v_mov_b32_e32 v114, v0
	v_mov_b32_e32 v115, v0
	v_mov_b32_e32 v116, v0
	v_mov_b32_e32 v117, v0
	v_mov_b32_e32 v118, v0
	v_mov_b32_e32 v119, v0
	v_mov_b32_e32 v72, v0
	v_mov_b32_e32 v73, v0
	v_mov_b32_e32 v74, v0
	v_mov_b32_e32 v75, v0
	v_mov_b32_e32 v76, v0
	v_mov_b32_e32 v77, v0
	v_mov_b32_e32 v78, v0
	v_mov_b32_e32 v79, v0
	v_mov_b32_e32 v88, v0
	v_mov_b32_e32 v89, v0
	v_mov_b32_e32 v90, v0
	v_mov_b32_e32 v91, v0
	v_mov_b32_e32 v92, v0
	v_mov_b32_e32 v93, v0
	v_mov_b32_e32 v94, v0
	v_mov_b32_e32 v95, v0
	v_mov_b32_e32 v104, v0
	v_mov_b32_e32 v105, v0
	v_mov_b32_e32 v106, v0
	v_mov_b32_e32 v107, v0
	v_mov_b32_e32 v108, v0
	v_mov_b32_e32 v109, v0
	v_mov_b32_e32 v110, v0
	v_mov_b32_e32 v111, v0
	v_mov_b32_e32 v120, v0
	v_mov_b32_e32 v121, v0
	v_mov_b32_e32 v122, v0
	v_mov_b32_e32 v123, v0
	v_mov_b32_e32 v124, v0
	v_mov_b32_e32 v125, v0
	v_mov_b32_e32 v126, v0
	v_mov_b32_e32 v127, v0

; template <class Epi, class Sched, bool ALIGN_EPI = false, bool SP2 = false>
; __device__ __forceinline__ void gemm_phase(PG8_LAS unsigned char* lds, const Gemm g, const Sched& S, const Epi& E, const int tid_in) {
;     ...
;         for (int t = 0; t < nt; t += 2) {
;             const bool last = (t == nt - 2);
;             const char* a1 = cA + (size_t)(t + 1) * kstep;
;             const char* a2 = last ? nA : cA + (size_t)(t + 2) * kstep; const char* b2 = last ? nB : cB + (size_t)(t + 2) * kstep;
;             const char* a3 = a2 + kstep; const char* b3 = b2 + kstep;
;     ...
; #pragma unroll
;         for (int a = 0; a < 2; ++a)
; #pragma unroll
;             for (int b = 0; b < 2; ++b)
; #pragma unroll
;                 for (int m = 0; m < 4; ++m)
; #pragma unroll
;                     for (int n = 0; n < 2; ++n) acc[a][b][m][n] = (f32x4){0.f, 0.f, 0.f, 0.f};
;         cur = nxt; cA = nA; cB = nB; ++ui;
.LBB0_706:
	s_andn2_b64 vcc, exec, s[12:13]
	s_cbranch_vccnz .Lzk_8
	s_add_u32 s18, s18, 0x80
	s_addc_u32 s19, s19, 0
	s_add_u32 s47, s20, 0x100
	v_mov_b32_e32 v0, 0
	s_addc_u32 s48, s21, 0
	s_mov_b32 s20, 0
	v_mov_b32_e32 v1, v0
	v_mov_b32_e32 v2, v0
	v_mov_b32_e32 v3, v0
	v_mov_b32_e32 v4, v0
	v_mov_b32_e32 v5, v0
	v_mov_b32_e32 v6, v0
	v_mov_b32_e32 v7, v0
	v_mov_b32_e32 v16, v0
	v_mov_b32_e32 v17, v0
	v_mov_b32_e32 v18, v0
	v_mov_b32_e32 v19, v0
	v_mov_b32_e32 v20, v0
	v_mov_b32_e32 v21, v0
	v_mov_b32_e32 v22, v0
	v_mov_b32_e32 v23, v0
	v_mov_b32_e32 v32, v0
	v_mov_b32_e32 v33, v0
	v_mov_b32_e32 v34, v0
	v_mov_b32_e32 v35, v0
	v_mov_b32_e32 v36, v0
	v_mov_b32_e32 v37, v0
	v_mov_b32_e32 v38, v0
	v_mov_b32_e32 v39, v0
	v_mov_b32_e32 v48, v0
	v_mov_b32_e32 v49, v0
	v_mov_b32_e32 v50, v0
	v_mov_b32_e32 v51, v0
	v_mov_b32_e32 v52, v0
	v_mov_b32_e32 v53, v0
	v_mov_b32_e32 v54, v0
	v_mov_b32_e32 v55, v0
	v_mov_b32_e32 v8, v0
	v_mov_b32_e32 v9, v0
	v_mov_b32_e32 v10, v0
	v_mov_b32_e32 v11, v0
	v_mov_b32_e32 v12, v0
	v_mov_b32_e32 v13, v0
	v_mov_b32_e32 v14, v0
	v_mov_b32_e32 v15, v0
	v_mov_b32_e32 v24, v0
	v_mov_b32_e32 v25, v0
	v_mov_b32_e32 v26, v0
	v_mov_b32_e32 v27, v0
	v_mov_b32_e32 v28, v0
	v_mov_b32_e32 v29, v0
	v_mov_b32_e32 v30, v0
	v_mov_b32_e32 v31, v0
	v_mov_b32_e32 v40, v0
	v_mov_b32_e32 v41, v0
	v_mov_b32_e32 v42, v0
	v_mov_b32_e32 v43, v0
	v_mov_b32_e32 v44, v0
	v_mov_b32_e32 v45, v0
	v_mov_b32_e32 v46, v0
	v_mov_b32_e32 v47, v0
	v_mov_b32_e32 v56, v0
	v_mov_b32_e32 v57, v0
	v_mov_b32_e32 v58, v0
	v_mov_b32_e32 v59, v0
	v_mov_b32_e32 v60, v0
	v_mov_b32_e32 v61, v0
	v_mov_b32_e32 v62, v0
	v_mov_b32_e32 v63, v0
	v_mov_b32_e32 v64, v0
	v_mov_b32_e32 v65, v0
	v_mov_b32_e32 v66, v0
	v_mov_b32_e32 v67, v0
	v_mov_b32_e32 v68, v0
	v_mov_b32_e32 v69, v0
	v_mov_b32_e32 v70, v0
	v_mov_b32_e32 v71, v0
	v_mov_b32_e32 v80, v0
	v_mov_b32_e32 v81, v0
	v_mov_b32_e32 v82, v0
	v_mov_b32_e32 v83, v0
	v_mov_b32_e32 v84, v0
	v_mov_b32_e32 v85, v0
	v_mov_b32_e32 v86, v0
	v_mov_b32_e32 v87, v0
	v_mov_b32_e32 v96, v0
	v_mov_b32_e32 v97, v0
	v_mov_b32_e32 v98, v0
	v_mov_b32_e32 v99, v0
	v_mov_b32_e32 v100, v0
	v_mov_b32_e32 v101, v0
	v_mov_b32_e32 v102, v0
	v_mov_b32_e32 v103, v0
	v_mov_b32_e32 v112, v0
	v_mov_b32_e32 v113, v0
	v_mov_b32_e32 v114, v0
	v_mov_b32_e32 v115, v0
	v_mov_b32_e32 v116, v0
	v_mov_b32_e32 v117, v0
	v_mov_b32_e32 v118, v0
	v_mov_b32_e32 v119, v0
	v_mov_b32_e32 v72, v0
	v_mov_b32_e32 v73, v0
	v_mov_b32_e32 v74, v0
	v_mov_b32_e32 v75, v0
	v_mov_b32_e32 v76, v0
	v_mov_b32_e32 v77, v0
	v_mov_b32_e32 v78, v0
	v_mov_b32_e32 v79, v0
	v_mov_b32_e32 v88, v0
	v_mov_b32_e32 v89, v0
	v_mov_b32_e32 v90, v0
	v_mov_b32_e32 v91, v0
	v_mov_b32_e32 v92, v0
	v_mov_b32_e32 v93, v0
	v_mov_b32_e32 v94, v0
	v_mov_b32_e32 v95, v0
	v_mov_b32_e32 v104, v0
	v_mov_b32_e32 v105, v0
	v_mov_b32_e32 v106, v0
	v_mov_b32_e32 v107, v0
	v_mov_b32_e32 v108, v0
	v_mov_b32_e32 v109, v0
	v_mov_b32_e32 v110, v0
	v_mov_b32_e32 v111, v0
	v_mov_b32_e32 v124, v0
	v_mov_b32_e32 v125, v0
	v_mov_b32_e32 v126, v0
	v_mov_b32_e32 v127, v0
	v_mov_b32_e32 v120, v0
	v_mov_b32_e32 v121, v0
	v_mov_b32_e32 v122, v0
	v_mov_b32_e32 v123, v0

; template <class Epi, class Sched, bool ALIGN_EPI = false, bool SP2 = false>
; __device__ __forceinline__ void gemm_phase(PG8_LAS unsigned char* lds, const Gemm g, const Sched& S, const Epi& E, const int tid_in) {
;     ...
;         for (int t = 0; t < nt; t += 2) {
;             const bool last = (t == nt - 2);
;             const char* a1 = cA + (size_t)(t + 1) * kstep;
;             const char* a2 = last ? nA : cA + (size_t)(t + 2) * kstep; const char* b2 = last ? nB : cB + (size_t)(t + 2) * kstep;
;             const char* a3 = a2 + kstep; const char* b3 = b2 + kstep;
;     ...
; #pragma unroll
;         for (int a = 0; a < 2; ++a)
; #pragma unroll
;             for (int b = 0; b < 2; ++b)
; #pragma unroll
;                 for (int m = 0; m < 4; ++m)
; #pragma unroll
;                     for (int n = 0; n < 2; ++n) acc[a][b][m][n] = (f32x4){0.f, 0.f, 0.f, 0.f};
;         cur = nxt; cA = nA; cB = nB; ++ui;
.LBB0_729:
	s_andn2_b64 vcc, exec, s[10:11]
	s_cbranch_vccnz .Lzk_9
	s_add_u32 s16, s16, 0x80
	s_addc_u32 s17, s17, 0
	s_add_u32 s42, s18, 0x100
	v_mov_b32_e32 v0, 0
	s_addc_u32 s43, s19, 0
	s_mov_b32 s18, 0
	v_mov_b32_e32 v1, v0
	v_mov_b32_e32 v2, v0
	v_mov_b32_e32 v3, v0
	v_mov_b32_e32 v4, v0
	v_mov_b32_e32 v5, v0
	v_mov_b32_e32 v6, v0
	v_mov_b32_e32 v7, v0
	v_mov_b32_e32 v16, v0
	v_mov_b32_e32 v17, v0
	v_mov_b32_e32 v18, v0
	v_mov_b32_e32 v19, v0
	v_mov_b32_e32 v20, v0
	v_mov_b32_e32 v21, v0
	v_mov_b32_e32 v22, v0
	v_mov_b32_e32 v23, v0
	v_mov_b32_e32 v32, v0
	v_mov_b32_e32 v33, v0
	v_mov_b32_e32 v34, v0
	v_mov_b32_e32 v35, v0
	v_mov_b32_e32 v36, v0
	v_mov_b32_e32 v37, v0
	v_mov_b32_e32 v38, v0
	v_mov_b32_e32 v39, v0
	v_mov_b32_e32 v48, v0
	v_mov_b32_e32 v49, v0
	v_mov_b32_e32 v50, v0
	v_mov_b32_e32 v51, v0
	v_mov_b32_e32 v52, v0
	v_mov_b32_e32 v53, v0
	v_mov_b32_e32 v54, v0
	v_mov_b32_e32 v55, v0
	v_mov_b32_e32 v8, v0
	v_mov_b32_e32 v9, v0
	v_mov_b32_e32 v10, v0
	v_mov_b32_e32 v11, v0
	v_mov_b32_e32 v12, v0
	v_mov_b32_e32 v13, v0
	v_mov_b32_e32 v14, v0
	v_mov_b32_e32 v15, v0
	v_mov_b32_e32 v24, v0
	v_mov_b32_e32 v25, v0
	v_mov_b32_e32 v26, v0
	v_mov_b32_e32 v27, v0
	v_mov_b32_e32 v28, v0
	v_mov_b32_e32 v29, v0
	v_mov_b32_e32 v30, v0
	v_mov_b32_e32 v31, v0
	v_mov_b32_e32 v40, v0
	v_mov_b32_e32 v41, v0
	v_mov_b32_e32 v42, v0
	v_mov_b32_e32 v43, v0
	v_mov_b32_e32 v44, v0
	v_mov_b32_e32 v45, v0
	v_mov_b32_e32 v46, v0
	v_mov_b32_e32 v47, v0
	v_mov_b32_e32 v56, v0
	v_mov_b32_e32 v57, v0
	v_mov_b32_e32 v58, v0
	v_mov_b32_e32 v59, v0
	v_mov_b32_e32 v60, v0
	v_mov_b32_e32 v61, v0
	v_mov_b32_e32 v62, v0
	v_mov_b32_e32 v63, v0
	v_mov_b32_e32 v64, v0
	v_mov_b32_e32 v65, v0
	v_mov_b32_e32 v66, v0
	v_mov_b32_e32 v67, v0
	v_mov_b32_e32 v68, v0
	v_mov_b32_e32 v69, v0
	v_mov_b32_e32 v70, v0
	v_mov_b32_e32 v71, v0
	v_mov_b32_e32 v80, v0
	v_mov_b32_e32 v81, v0
	v_mov_b32_e32 v82, v0
	v_mov_b32_e32 v83, v0
	v_mov_b32_e32 v84, v0
	v_mov_b32_e32 v85, v0
	v_mov_b32_e32 v86, v0
	v_mov_b32_e32 v87, v0
	v_mov_b32_e32 v96, v0
	v_mov_b32_e32 v97, v0
	v_mov_b32_e32 v98, v0
	v_mov_b32_e32 v99, v0
	v_mov_b32_e32 v100, v0
	v_mov_b32_e32 v101, v0
	v_mov_b32_e32 v102, v0
	v_mov_b32_e32 v103, v0
	v_mov_b32_e32 v112, v0
	v_mov_b32_e32 v113, v0
	v_mov_b32_e32 v114, v0
	v_mov_b32_e32 v115, v0
	v_mov_b32_e32 v116, v0
	v_mov_b32_e32 v117, v0
	v_mov_b32_e32 v118, v0
	v_mov_b32_e32 v119, v0
	v_mov_b32_e32 v72, v0
	v_mov_b32_e32 v73, v0
	v_mov_b32_e32 v74, v0
	v_mov_b32_e32 v75, v0
	v_mov_b32_e32 v76, v0
	v_mov_b32_e32 v77, v0
	v_mov_b32_e32 v78, v0
	v_mov_b32_e32 v79, v0
	v_mov_b32_e32 v88, v0
	v_mov_b32_e32 v89, v0
	v_mov_b32_e32 v90, v0
	v_mov_b32_e32 v91, v0
	v_mov_b32_e32 v92, v0
	v_mov_b32_e32 v93, v0
	v_mov_b32_e32 v94, v0
	v_mov_b32_e32 v95, v0
	v_mov_b32_e32 v104, v0
	v_mov_b32_e32 v105, v0
	v_mov_b32_e32 v106, v0
	v_mov_b32_e32 v107, v0
	v_mov_b32_e32 v108, v0
	v_mov_b32_e32 v109, v0
	v_mov_b32_e32 v110, v0
	v_mov_b32_e32 v111, v0
	v_mov_b32_e32 v124, v0
	v_mov_b32_e32 v125, v0
	v_mov_b32_e32 v126, v0
	v_mov_b32_e32 v127, v0
	v_mov_b32_e32 v120, v0
	v_mov_b32_e32 v121, v0
	v_mov_b32_e32 v122, v0
	v_mov_b32_e32 v123, v0
